# W_out and W_in GEMM K loops shifted by 4 bytes so that their MFMA runs start on 8-byte boundaries like the fc1/fc2 loops
# speedup vs baseline: 1.0053x; 1.0053x over previous
.LBB0_169:
	s_ashr_i32 s43, s42, 31
	s_lshl_b64 s[20:21], s[42:43], 19
	v_readlane_b32 s24, v254, 43
	v_cmp_lt_i64_e32 vcc, s[44:45], v[186:187]
	v_readlane_b32 s25, v254, 44
	s_add_u32 s44, s24, s20
	s_addc_u32 s45, s25, s21
	s_and_b64 s[20:21], vcc, exec
	s_cselect_b32 s43, s45, s49
	s_cselect_b32 s24, s44, s48
	s_ashr_i32 s1, s0, 31
	s_lshl_b64 s[20:21], s[0:1], 19
	v_readlane_b32 s46, v254, 41
	v_readlane_b32 s47, v254, 42
	s_add_u32 s46, s46, s20
	s_addc_u32 s47, s47, s21
	s_and_b64 s[20:21], vcc, exec
	s_cselect_b32 s1, s47, s29
	s_cselect_b32 s25, s46, s28
	s_add_u32 s48, s48, 0x40080
	s_addc_u32 s49, s49, 0
	s_add_u32 vcc_lo, s28, 0x100
	v_mov_b32_e32 v0, 0
	s_mov_b64 s[92:93], s[74:75]
	s_addc_u32 vcc_hi, s29, 0
	s_mov_b32 s57, -2
	v_mov_b32_e32 v1, v0
	v_mov_b64_e32 v[2:3], 0
	v_mov_b64_e32 v[4:5], 0
	v_mov_b64_e32 v[6:7], 0
	v_mov_b64_e32 v[16:17], 0
	v_mov_b64_e32 v[18:19], 0
	v_mov_b64_e32 v[20:21], 0
	v_mov_b64_e32 v[22:23], 0
	v_mov_b64_e32 v[32:33], 0
	v_mov_b64_e32 v[34:35], 0
	v_mov_b64_e32 v[36:37], 0
	v_mov_b64_e32 v[38:39], 0
	v_mov_b64_e32 v[48:49], 0
	v_mov_b64_e32 v[50:51], 0
	v_mov_b64_e32 v[52:53], 0
	v_mov_b64_e32 v[54:55], 0
	v_mov_b64_e32 v[8:9], 0
	v_mov_b64_e32 v[10:11], 0
	v_mov_b64_e32 v[12:13], 0
	v_mov_b64_e32 v[14:15], 0
	v_mov_b64_e32 v[24:25], 0
	v_mov_b64_e32 v[26:27], 0
	v_mov_b64_e32 v[28:29], 0
	v_mov_b64_e32 v[30:31], 0
	v_mov_b64_e32 v[40:41], 0
	v_mov_b64_e32 v[42:43], 0
	v_mov_b64_e32 v[44:45], 0
	v_mov_b64_e32 v[46:47], 0
	v_mov_b64_e32 v[56:57], 0
	v_mov_b64_e32 v[58:59], 0
	v_mov_b64_e32 v[60:61], 0
	v_mov_b64_e32 v[62:63], 0
	v_mov_b64_e32 v[64:65], 0
	v_mov_b64_e32 v[66:67], 0
	v_mov_b64_e32 v[68:69], 0
	v_mov_b64_e32 v[70:71], 0
	v_mov_b64_e32 v[80:81], 0
	v_mov_b64_e32 v[82:83], 0
	v_mov_b64_e32 v[84:85], 0
	v_mov_b64_e32 v[86:87], 0
	v_mov_b64_e32 v[96:97], 0
	v_mov_b64_e32 v[98:99], 0
	v_mov_b64_e32 v[100:101], 0
	v_mov_b64_e32 v[102:103], 0
	v_mov_b64_e32 v[112:113], 0
	v_mov_b64_e32 v[114:115], 0
	v_mov_b64_e32 v[116:117], 0
	v_mov_b64_e32 v[118:119], 0
	v_mov_b64_e32 v[72:73], 0
	v_mov_b64_e32 v[74:75], 0
	v_mov_b64_e32 v[76:77], 0
	v_mov_b64_e32 v[78:79], 0
	v_mov_b64_e32 v[88:89], 0
	v_mov_b64_e32 v[90:91], 0
	v_mov_b64_e32 v[92:93], 0
	v_mov_b64_e32 v[94:95], 0
	v_mov_b64_e32 v[104:105], 0
	v_mov_b64_e32 v[106:107], 0
	v_mov_b64_e32 v[108:109], 0
	v_mov_b64_e32 v[110:111], 0
	v_mov_b64_e32 v[120:121], 0
	v_mov_b64_e32 v[122:123], 0
	v_mov_b64_e32 v[124:125], 0
	v_mov_b64_e32 v[126:127], 0
	s_nop 0
.LBB0_170:
	s_add_u32 s20, s48, 0xfffc0080
	s_addc_u32 s21, s49, -1
	s_add_i32 s60, 0, 0x10000
	v_add_u32_e32 v140, s60, v232
	ds_read_b128 v[128:131], v140
	ds_read_b128 v[132:135], v140 offset:1024
	ds_read_b128 v[136:139], v140 offset:2048
	ds_read_b128 v[140:143], v140 offset:3072
	s_cmp_eq_u32 s57, 12
	s_cselect_b32 s51, s43, s21
	s_cselect_b32 s50, s24, s20
	s_cselect_b32 s29, s1, vcc_hi
	s_cselect_b32 s28, s25, vcc_lo
	s_add_i32 m0, s55, 0xc000
	ds_read_b128 v[144:147], v234
	ds_read_b128 v[148:151], v234 offset:1024
	ds_read_b128 v[152:155], v234 offset:2048
	ds_read_b128 v[156:159], v234 offset:3072
	ds_read_b128 v[160:163], v234 offset:4096
	ds_read_b128 v[164:167], v234 offset:5120
	ds_read_b128 v[168:171], v234 offset:6144
	ds_read_b128 v[172:175], v234 offset:7168
	global_load_lds_dwordx4 v204, s[48:49]
	s_add_i32 m0, s55, 0xe000
	s_nop 0
	global_load_lds_dwordx4 v206, s[48:49]
	s_waitcnt lgkmcnt(8)
	s_barrier
	s_waitcnt lgkmcnt(0)
	v_mfma_f32_16x16x32_bf16 v[124:127], v[128:131], v[144:147], v[124:127]
	v_mfma_f32_16x16x32_bf16 v[120:123], v[136:139], v[144:147], v[120:123]
	v_mfma_f32_16x16x32_bf16 v[108:111], v[128:131], v[152:155], v[108:111]
	v_mfma_f32_16x16x32_bf16 v[104:107], v[136:139], v[152:155], v[104:107]
	v_mfma_f32_16x16x32_bf16 v[92:95], v[128:131], v[160:163], v[92:95]
	v_mfma_f32_16x16x32_bf16 v[88:91], v[136:139], v[160:163], v[88:91]
	v_mfma_f32_16x16x32_bf16 v[76:79], v[128:131], v[168:171], v[76:79]
	v_mfma_f32_16x16x32_bf16 v[72:75], v[136:139], v[168:171], v[72:75]
	v_mfma_f32_16x16x32_bf16 v[124:127], v[132:135], v[148:151], v[124:127]
	v_mfma_f32_16x16x32_bf16 v[120:123], v[140:143], v[148:151], v[120:123]
	v_mfma_f32_16x16x32_bf16 v[108:111], v[132:135], v[156:159], v[108:111]
	v_mfma_f32_16x16x32_bf16 v[104:107], v[140:143], v[156:159], v[104:107]
	v_mfma_f32_16x16x32_bf16 v[92:95], v[132:135], v[164:167], v[92:95]
	v_mfma_f32_16x16x32_bf16 v[88:91], v[140:143], v[164:167], v[88:91]
	v_mfma_f32_16x16x32_bf16 v[76:79], v[132:135], v[172:175], v[76:79]
	v_mfma_f32_16x16x32_bf16 v[72:75], v[140:143], v[172:175], v[72:75]
	s_barrier
	s_add_i32 s61, 0, 0x14000
	v_add_u32_e32 v184, s61, v232
	s_add_i32 s20, s60, s54
	ds_read_b128 v[208:211], v184
	ds_read_b128 v[212:215], v184 offset:1024
	ds_read_b128 v[216:219], v184 offset:2048
	ds_read_b128 v[236:239], v184 offset:3072
	s_add_u32 s72, s28, s52
	s_addc_u32 s73, s29, s53
	s_mov_b32 m0, s20
	s_nop 0
	global_load_lds_dwordx4 v176, s[28:29]
	s_add_i32 m0, s20, 0x2000
	s_nop 0
	global_load_lds_dwordx4 v198, s[28:29]
	s_barrier
	s_waitcnt lgkmcnt(0)
	v_mfma_f32_16x16x32_bf16 v[116:119], v[208:211], v[144:147], v[116:119]
	v_mfma_f32_16x16x32_bf16 v[112:115], v[216:219], v[144:147], v[112:115]
	v_mfma_f32_16x16x32_bf16 v[100:103], v[208:211], v[152:155], v[100:103]
	v_mfma_f32_16x16x32_bf16 v[96:99], v[216:219], v[152:155], v[96:99]
	v_mfma_f32_16x16x32_bf16 v[84:87], v[208:211], v[160:163], v[84:87]
	v_mfma_f32_16x16x32_bf16 v[80:83], v[216:219], v[160:163], v[80:83]
	v_mfma_f32_16x16x32_bf16 v[68:71], v[208:211], v[168:171], v[68:71]
	v_mfma_f32_16x16x32_bf16 v[64:67], v[216:219], v[168:171], v[64:67]
	v_mfma_f32_16x16x32_bf16 v[116:119], v[212:215], v[148:151], v[116:119]
	v_mfma_f32_16x16x32_bf16 v[112:115], v[236:239], v[148:151], v[112:115]
	v_mfma_f32_16x16x32_bf16 v[100:103], v[212:215], v[156:159], v[100:103]
	v_mfma_f32_16x16x32_bf16 v[96:99], v[236:239], v[156:159], v[96:99]
	v_mfma_f32_16x16x32_bf16 v[84:87], v[212:215], v[164:167], v[84:87]
	v_mfma_f32_16x16x32_bf16 v[80:83], v[236:239], v[164:167], v[80:83]
	v_mfma_f32_16x16x32_bf16 v[68:71], v[212:215], v[172:175], v[68:71]
	v_mfma_f32_16x16x32_bf16 v[64:67], v[236:239], v[172:175], v[64:67]
	s_mov_b32 m0, s55
	s_add_u32 s70, s50, s52
	s_addc_u32 s71, s51, s53
	s_barrier
	ds_read_b128 v[144:147], v234 offset:16384
	ds_read_b128 v[148:151], v234 offset:17408
	ds_read_b128 v[152:155], v234 offset:18432
	ds_read_b128 v[156:159], v234 offset:19456
	ds_read_b128 v[160:163], v234 offset:20480
	ds_read_b128 v[164:167], v234 offset:21504
	ds_read_b128 v[168:171], v234 offset:22528
	ds_read_b128 v[172:175], v234 offset:23552
	global_load_lds_dwordx4 v202, s[50:51]
	s_mov_b32 m0, s56
	s_nop 0
	global_load_lds_dwordx4 v200, s[50:51]
	s_barrier
	s_waitcnt lgkmcnt(0)
	v_mfma_f32_16x16x32_bf16 v[60:63], v[128:131], v[144:147], v[60:63]
	v_mfma_f32_16x16x32_bf16 v[56:59], v[136:139], v[144:147], v[56:59]
	v_mfma_f32_16x16x32_bf16 v[44:47], v[128:131], v[152:155], v[44:47]
	v_mfma_f32_16x16x32_bf16 v[40:43], v[136:139], v[152:155], v[40:43]
	v_mfma_f32_16x16x32_bf16 v[28:31], v[128:131], v[160:163], v[28:31]
	v_mfma_f32_16x16x32_bf16 v[24:27], v[136:139], v[160:163], v[24:27]
	v_mfma_f32_16x16x32_bf16 v[12:15], v[128:131], v[168:171], v[12:15]
	v_mfma_f32_16x16x32_bf16 v[8:11], v[136:139], v[168:171], v[8:11]
	v_mfma_f32_16x16x32_bf16 v[60:63], v[132:135], v[148:151], v[60:63]
	v_mfma_f32_16x16x32_bf16 v[56:59], v[140:143], v[148:151], v[56:59]
	v_mfma_f32_16x16x32_bf16 v[44:47], v[132:135], v[156:159], v[44:47]
	v_mfma_f32_16x16x32_bf16 v[40:43], v[140:143], v[156:159], v[40:43]
	v_mfma_f32_16x16x32_bf16 v[28:31], v[132:135], v[164:167], v[28:31]
	v_mfma_f32_16x16x32_bf16 v[24:27], v[140:143], v[164:167], v[24:27]
	v_mfma_f32_16x16x32_bf16 v[12:15], v[132:135], v[172:175], v[12:15]
	v_mfma_f32_16x16x32_bf16 v[8:11], v[140:143], v[172:175], v[8:11]
	s_barrier
	s_add_u32 s20, s28, 0x40000
	s_addc_u32 s21, s29, 0
	s_add_i32 s60, s61, s54
	s_mov_b32 m0, s60
	s_nop 0
	global_load_lds_dwordx4 v176, s[20:21]
	s_add_i32 m0, s60, 0x2000
	s_nop 0
	global_load_lds_dwordx4 v198, s[20:21]
	s_waitcnt vmcnt(6)
	s_barrier
	v_mfma_f32_16x16x32_bf16 v[52:55], v[208:211], v[144:147], v[52:55]
	v_mfma_f32_16x16x32_bf16 v[48:51], v[216:219], v[144:147], v[48:51]
	v_mfma_f32_16x16x32_bf16 v[36:39], v[208:211], v[152:155], v[36:39]
	v_mfma_f32_16x16x32_bf16 v[32:35], v[216:219], v[152:155], v[32:35]
	v_mfma_f32_16x16x32_bf16 v[20:23], v[208:211], v[160:163], v[20:23]
	v_mfma_f32_16x16x32_bf16 v[16:19], v[216:219], v[160:163], v[16:19]
	v_mfma_f32_16x16x32_bf16 v[4:7], v[208:211], v[168:171], v[4:7]
	v_mfma_f32_16x16x32_bf16 v[0:3], v[216:219], v[168:171], v[0:3]
	v_mfma_f32_16x16x32_bf16 v[52:55], v[212:215], v[148:151], v[52:55]
	v_mfma_f32_16x16x32_bf16 v[48:51], v[236:239], v[148:151], v[48:51]
	v_mfma_f32_16x16x32_bf16 v[36:39], v[212:215], v[156:159], v[36:39]
	v_mfma_f32_16x16x32_bf16 v[32:35], v[236:239], v[156:159], v[32:35]
	v_mfma_f32_16x16x32_bf16 v[20:23], v[212:215], v[164:167], v[20:23]
	v_mfma_f32_16x16x32_bf16 v[16:19], v[236:239], v[164:167], v[16:19]
	v_mfma_f32_16x16x32_bf16 v[4:7], v[212:215], v[172:175], v[4:7]
	v_mfma_f32_16x16x32_bf16 v[0:3], v[236:239], v[172:175], v[0:3]
	s_add_i32 s60, 0, 0x18000
	v_add_u32_e32 v140, s60, v232
	s_barrier
	ds_read_b128 v[128:131], v140
	ds_read_b128 v[132:135], v140 offset:1024
	ds_read_b128 v[136:139], v140 offset:2048
	ds_read_b128 v[140:143], v140 offset:3072
	s_add_u32 s20, s50, 0x40000
	s_addc_u32 s21, s51, 0
	s_mov_b32 m0, s7
	ds_read_b128 v[144:147], v234 offset:32768
	ds_read_b128 v[148:151], v234 offset:33792
	ds_read_b128 v[152:155], v234 offset:34816
	ds_read_b128 v[156:159], v234 offset:35840
	ds_read_b128 v[160:163], v234 offset:36864
	ds_read_b128 v[164:167], v234 offset:37888
	ds_read_b128 v[168:171], v234 offset:38912
	ds_read_b128 v[172:175], v234 offset:39936
	global_load_lds_dwordx4 v202, s[20:21]
	s_mov_b32 m0, s15
	s_nop 0
	global_load_lds_dwordx4 v200, s[20:21]
	s_waitcnt lgkmcnt(8)
	s_barrier
	s_waitcnt lgkmcnt(0)
	v_mfma_f32_16x16x32_bf16 v[124:127], v[128:131], v[144:147], v[124:127]
	v_mfma_f32_16x16x32_bf16 v[120:123], v[136:139], v[144:147], v[120:123]
	v_mfma_f32_16x16x32_bf16 v[108:111], v[128:131], v[152:155], v[108:111]
	v_mfma_f32_16x16x32_bf16 v[104:107], v[136:139], v[152:155], v[104:107]
	v_mfma_f32_16x16x32_bf16 v[92:95], v[128:131], v[160:163], v[92:95]
	v_mfma_f32_16x16x32_bf16 v[88:91], v[136:139], v[160:163], v[88:91]
	v_mfma_f32_16x16x32_bf16 v[76:79], v[128:131], v[168:171], v[76:79]
	v_mfma_f32_16x16x32_bf16 v[72:75], v[136:139], v[168:171], v[72:75]
	v_mfma_f32_16x16x32_bf16 v[124:127], v[132:135], v[148:151], v[124:127]
	v_mfma_f32_16x16x32_bf16 v[120:123], v[140:143], v[148:151], v[120:123]
	v_mfma_f32_16x16x32_bf16 v[108:111], v[132:135], v[156:159], v[108:111]
	v_mfma_f32_16x16x32_bf16 v[104:107], v[140:143], v[156:159], v[104:107]
	v_mfma_f32_16x16x32_bf16 v[92:95], v[132:135], v[164:167], v[92:95]
	v_mfma_f32_16x16x32_bf16 v[88:91], v[140:143], v[164:167], v[88:91]
	v_mfma_f32_16x16x32_bf16 v[76:79], v[132:135], v[172:175], v[76:79]
	v_mfma_f32_16x16x32_bf16 v[72:75], v[140:143], v[172:175], v[72:75]
	s_barrier
	s_add_i32 s50, 0, 0x1c000
	s_add_i32 s20, s60, s54
	v_add_u32_e32 v235, s50, v232
	s_mov_b32 m0, s20
	ds_read_b128 v[208:211], v235
	ds_read_b128 v[212:215], v235 offset:1024
	ds_read_b128 v[216:219], v235 offset:2048
	ds_read_b128 v[236:239], v235 offset:3072
	global_load_lds_dwordx4 v176, s[72:73]
	s_add_i32 m0, s20, 0x2000
	s_nop 0
	global_load_lds_dwordx4 v198, s[72:73]
	s_barrier
	s_waitcnt lgkmcnt(0)
	v_mfma_f32_16x16x32_bf16 v[116:119], v[208:211], v[144:147], v[116:119]
	v_mfma_f32_16x16x32_bf16 v[112:115], v[216:219], v[144:147], v[112:115]
	v_mfma_f32_16x16x32_bf16 v[100:103], v[208:211], v[152:155], v[100:103]
	v_mfma_f32_16x16x32_bf16 v[96:99], v[216:219], v[152:155], v[96:99]
	v_mfma_f32_16x16x32_bf16 v[84:87], v[208:211], v[160:163], v[84:87]
	v_mfma_f32_16x16x32_bf16 v[80:83], v[216:219], v[160:163], v[80:83]
	v_mfma_f32_16x16x32_bf16 v[68:71], v[208:211], v[168:171], v[68:71]
	v_mfma_f32_16x16x32_bf16 v[64:67], v[216:219], v[168:171], v[64:67]
	v_mfma_f32_16x16x32_bf16 v[116:119], v[212:215], v[148:151], v[116:119]
	v_mfma_f32_16x16x32_bf16 v[112:115], v[236:239], v[148:151], v[112:115]
	v_mfma_f32_16x16x32_bf16 v[100:103], v[212:215], v[156:159], v[100:103]
	v_mfma_f32_16x16x32_bf16 v[96:99], v[236:239], v[156:159], v[96:99]
	v_mfma_f32_16x16x32_bf16 v[84:87], v[212:215], v[164:167], v[84:87]
	v_mfma_f32_16x16x32_bf16 v[80:83], v[236:239], v[164:167], v[80:83]
	v_mfma_f32_16x16x32_bf16 v[68:71], v[212:215], v[172:175], v[68:71]
	v_mfma_f32_16x16x32_bf16 v[64:67], v[236:239], v[172:175], v[64:67]
	s_mov_b32 m0, s3
	s_barrier
	ds_read_b128 v[144:147], v234 offset:49152
	ds_read_b128 v[148:151], v234 offset:50176
	ds_read_b128 v[152:155], v234 offset:51200
	ds_read_b128 v[156:159], v234 offset:52224
	ds_read_b128 v[160:163], v234 offset:53248
	ds_read_b128 v[164:167], v234 offset:54272
	ds_read_b128 v[168:171], v234 offset:55296
	ds_read_b128 v[172:175], v234 offset:56320
	global_load_lds_dwordx4 v202, s[70:71]
	s_mov_b32 m0, s6
	s_nop 0
	global_load_lds_dwordx4 v200, s[70:71]
	s_barrier
	s_waitcnt lgkmcnt(0)
	v_mfma_f32_16x16x32_bf16 v[60:63], v[128:131], v[144:147], v[60:63]
	v_mfma_f32_16x16x32_bf16 v[56:59], v[136:139], v[144:147], v[56:59]
	v_mfma_f32_16x16x32_bf16 v[44:47], v[128:131], v[152:155], v[44:47]
	v_mfma_f32_16x16x32_bf16 v[40:43], v[136:139], v[152:155], v[40:43]
	v_mfma_f32_16x16x32_bf16 v[28:31], v[128:131], v[160:163], v[28:31]
	v_mfma_f32_16x16x32_bf16 v[24:27], v[136:139], v[160:163], v[24:27]
	v_mfma_f32_16x16x32_bf16 v[12:15], v[128:131], v[168:171], v[12:15]
	v_mfma_f32_16x16x32_bf16 v[8:11], v[136:139], v[168:171], v[8:11]
	v_mfma_f32_16x16x32_bf16 v[60:63], v[132:135], v[148:151], v[60:63]
	v_mfma_f32_16x16x32_bf16 v[56:59], v[140:143], v[148:151], v[56:59]
	v_mfma_f32_16x16x32_bf16 v[44:47], v[132:135], v[156:159], v[44:47]
	v_mfma_f32_16x16x32_bf16 v[40:43], v[140:143], v[156:159], v[40:43]
	v_mfma_f32_16x16x32_bf16 v[28:31], v[132:135], v[164:167], v[28:31]
	v_mfma_f32_16x16x32_bf16 v[24:27], v[140:143], v[164:167], v[24:27]
	v_mfma_f32_16x16x32_bf16 v[12:15], v[132:135], v[172:175], v[12:15]
	v_mfma_f32_16x16x32_bf16 v[8:11], v[140:143], v[172:175], v[8:11]
	s_barrier
	s_add_u32 s20, s28, 0x40080
	s_addc_u32 s21, s29, 0
	s_add_i32 s28, s50, s54
	s_mov_b32 m0, s28
	s_nop 0
	global_load_lds_dwordx4 v176, s[20:21]
	s_add_i32 m0, s28, 0x2000
	s_nop 0
	global_load_lds_dwordx4 v198, s[20:21]
	s_waitcnt vmcnt(6)
	s_barrier
	v_mfma_f32_16x16x32_bf16 v[52:55], v[208:211], v[144:147], v[52:55]
	v_mfma_f32_16x16x32_bf16 v[48:51], v[216:219], v[144:147], v[48:51]
	v_mfma_f32_16x16x32_bf16 v[36:39], v[208:211], v[152:155], v[36:39]
	v_mfma_f32_16x16x32_bf16 v[32:35], v[216:219], v[152:155], v[32:35]
	v_mfma_f32_16x16x32_bf16 v[20:23], v[208:211], v[160:163], v[20:23]
	v_mfma_f32_16x16x32_bf16 v[16:19], v[216:219], v[160:163], v[16:19]
	v_mfma_f32_16x16x32_bf16 v[4:7], v[208:211], v[168:171], v[4:7]
	v_mfma_f32_16x16x32_bf16 v[0:3], v[216:219], v[168:171], v[0:3]
	v_mfma_f32_16x16x32_bf16 v[52:55], v[212:215], v[148:151], v[52:55]
	v_mfma_f32_16x16x32_bf16 v[48:51], v[236:239], v[148:151], v[48:51]
	v_mfma_f32_16x16x32_bf16 v[36:39], v[212:215], v[156:159], v[36:39]
	v_mfma_f32_16x16x32_bf16 v[32:35], v[236:239], v[156:159], v[32:35]
	v_mfma_f32_16x16x32_bf16 v[20:23], v[212:215], v[164:167], v[20:23]
	v_mfma_f32_16x16x32_bf16 v[16:19], v[236:239], v[164:167], v[16:19]
	v_mfma_f32_16x16x32_bf16 v[4:7], v[212:215], v[172:175], v[4:7]
	v_mfma_f32_16x16x32_bf16 v[0:3], v[236:239], v[172:175], v[0:3]
	s_add_i32 s57, s57, 2
	s_add_u32 s48, s48, 0x100
	s_addc_u32 s49, s49, 0
	s_add_u32 vcc_lo, vcc_lo, 0x100
	s_addc_u32 vcc_hi, vcc_hi, 0
	s_cmp_gt_u32 s57, 13
	s_barrier
	s_cbranch_scc0 .LBB0_170
	s_nop 0
	v_lshl_add_u32 v210, s2, 8, v231
	v_lshl_or_b32 v208, s34, 8, v233
	v_readlane_b32 s60, v252, 10
	v_ashrrev_i32_e32 v209, 31, v208
	v_readlane_b32 s61, v252, 11
	v_ashrrev_i32_e32 v211, 31, v210
	v_lshlrev_b64 v[128:129], 12, v[210:211]
	v_lshl_add_u64 v[212:213], v[208:209], 2, s[60:61]
	v_lshl_add_u64 v[128:129], v[212:213], 0, v[128:129]
	global_load_dwordx4 v[236:239], v[128:129], off offset:16
	global_load_dwordx4 v[240:243], v[128:129], off
	global_load_dwordx4 v[244:247], v[128:129], off offset:528
	global_load_dwordx4 v[248:251], v[128:129], off offset:512
	v_or_b32_e32 v218, 16, v210
	v_ashrrev_i32_e32 v219, 31, v218
	v_lshlrev_b64 v[128:129], 12, v[218:219]
	v_or_b32_e32 v216, 32, v210
	v_lshl_add_u64 v[128:129], v[212:213], 0, v[128:129]
	v_ashrrev_i32_e32 v217, 31, v216
	global_load_dwordx4 v[168:171], v[128:129], off offset:16
	global_load_dwordx4 v[172:175], v[128:129], off
	global_load_dwordx4 v[160:163], v[128:129], off offset:528
	global_load_dwordx4 v[164:167], v[128:129], off offset:512
	v_lshlrev_b64 v[128:129], 12, v[216:217]
	v_or_b32_e32 v214, 48, v210
	v_lshl_add_u64 v[128:129], v[212:213], 0, v[128:129]
	v_ashrrev_i32_e32 v215, 31, v214
	global_load_dwordx4 v[152:155], v[128:129], off offset:16
	global_load_dwordx4 v[156:159], v[128:129], off
	global_load_dwordx4 v[136:139], v[128:129], off offset:528
	global_load_dwordx4 v[144:147], v[128:129], off offset:512
	v_lshlrev_b64 v[128:129], 12, v[214:215]
	v_lshl_add_u64 v[132:133], v[212:213], 0, v[128:129]
	global_load_dwordx4 v[140:143], v[132:133], off offset:16
	global_load_dwordx4 v[148:151], v[132:133], off
	global_load_dwordx4 v[128:131], v[132:133], off offset:528
	s_nop 0
	global_load_dwordx4 v[132:135], v[132:133], off offset:512
	v_readlane_b32 s68, v252, 18
	v_readlane_b32 s69, v252, 19
	v_readlane_b32 s68, v255, 14
	v_readlane_b32 s69, v255, 15
	s_lshl_b32 s48, s34, 2
	s_ashr_i32 s49, s48, 31
	v_readlane_b32 s62, v252, 12
	v_readlane_b32 s63, v252, 13
	v_readlane_b32 s64, v252, 14
	v_readlane_b32 s65, v252, 15
	v_readlane_b32 s66, v252, 16
	v_readlane_b32 s67, v252, 17
	v_readlane_b32 s70, v252, 20
	v_readlane_b32 s71, v252, 21
	v_readlane_b32 s72, v252, 22
	v_readlane_b32 s73, v252, 23
	v_readlane_b32 s74, v252, 24
	v_readlane_b32 s75, v252, 25
	s_waitcnt vmcnt(0)
	v_pk_add_f32 v[184:185], v[122:123], v[238:239]
	v_pk_add_f32 v[122:123], v[120:121], v[236:237]
	v_pk_add_f32 v[124:125], v[124:125], v[240:241]
	v_mul_f32_e32 v120, v122, v122
	v_mul_f32_e32 v121, v123, v123
	v_fmac_f32_e32 v120, v124, v124
	v_fmac_f32_e32 v121, v125, v125
	v_pk_add_f32 v[126:127], v[126:127], v[242:243]
	v_add_f32_e32 v120, v120, v121
	v_mul_f32_e32 v121, v184, v184
	v_fmac_f32_e32 v121, v126, v126
	v_add_f32_e32 v120, v121, v120
	v_mul_f32_e32 v121, v185, v185
	v_fmac_f32_e32 v121, v127, v127
	v_add_f32_e32 v192, v121, v120
	v_cvt_pk_bf16_f32 v120, v124, v125
	v_lshlrev_b64 v[124:125], 11, v[210:211]
	v_lshl_add_u64 v[124:125], s[68:69], 0, v[124:125]
	v_cvt_pk_bf16_f32 v121, v126, v127
	v_lshl_add_u64 v[124:125], v[208:209], 1, v[124:125]
	v_cvt_pk_bf16_f32 v122, v122, v123
	v_cvt_pk_bf16_f32 v123, v184, v185
	global_store_dwordx4 v[124:125], v[120:123], off
	v_pk_add_f32 v[116:117], v[116:117], v[248:249]
	v_pk_add_f32 v[118:119], v[118:119], v[250:251]
	v_pk_add_f32 v[120:121], v[114:115], v[246:247]
	v_pk_add_f32 v[114:115], v[112:113], v[244:245]
	s_nop 0
	v_mul_f32_e32 v112, v114, v114
	v_fmac_f32_e32 v112, v116, v116
	v_mul_f32_e32 v113, v115, v115
	v_add_f32_e32 v112, v112, v192
	v_fmac_f32_e32 v113, v117, v117
	v_add_f32_e32 v112, v113, v112
	v_mul_f32_e32 v113, v120, v120
	v_fmac_f32_e32 v113, v118, v118
	v_add_f32_e32 v112, v113, v112
	v_mul_f32_e32 v113, v121, v121
	v_fmac_f32_e32 v113, v119, v119
	v_add_f32_e32 v122, v113, v112
	v_cvt_pk_bf16_f32 v112, v116, v117
	v_cvt_pk_bf16_f32 v113, v118, v119
	v_cvt_pk_bf16_f32 v114, v114, v115
	v_cvt_pk_bf16_f32 v115, v120, v121
	global_store_dwordx4 v[124:125], v[112:115], off offset:256
	s_nop 1
	v_and_b32_e32 v113, 64, v225
	v_xor_b32_e32 v112, 16, v225
	v_add_u32_e32 v113, 64, v113
	v_cmp_lt_i32_e32 vcc, v112, v113
	v_xor_b32_e32 v114, 32, v225
	s_nop 0
	v_cndmask_b32_e32 v112, v225, v112, vcc
	v_lshlrev_b32_e32 v235, 2, v112
	ds_bpermute_b32 v112, v235, v122
	v_cmp_lt_i32_e32 vcc, v114, v113
	s_waitcnt lgkmcnt(0)
	v_add_f32_e32 v112, v122, v112
	v_cndmask_b32_e32 v113, v225, v114, vcc
	v_lshlrev_b32_e32 v236, 2, v113
	ds_bpermute_b32 v113, v236, v112
	s_and_saveexec_b64 s[28:29], s[38:39]
	s_cbranch_execz .LBB0_173
	v_readlane_b32 s20, v253, 31
	v_lshlrev_b64 v[114:115], 6, v[210:211]
	v_readlane_b32 s21, v253, 32
	s_lshl_b32 s34, s58, 2
	s_waitcnt lgkmcnt(0)
	v_add_f32_e32 v112, v112, v113
	v_lshl_add_u64 v[114:115], s[20:21], 0, v[114:115]
	v_lshl_add_u64 v[114:115], s[48:49], 2, v[114:115]
	v_lshl_add_u64 v[114:115], v[114:115], 0, s[34:35]
	global_store_dword v[114:115], v112, off

.LBB0_291:
	s_ashr_i32 s41, s40, 31
	v_mov_b64_e32 v[0:1], 0x400
	s_lshl_b64 s[20:21], s[40:41], 19
	v_readlane_b32 s24, v254, 15
	v_cmp_lt_i64_e32 vcc, s[42:43], v[0:1]
	v_readlane_b32 s25, v254, 16
	s_add_u32 s42, s24, s20
	s_addc_u32 s43, s25, s21
	s_and_b64 s[20:21], vcc, exec
	s_cselect_b32 s41, s43, s47
	s_cselect_b32 s24, s42, s46
	s_ashr_i32 s1, s0, 31
	s_lshl_b64 s[20:21], s[0:1], 19
	v_readlane_b32 s44, v254, 13
	v_readlane_b32 s45, v254, 14
	s_add_u32 s44, s44, s20
	s_addc_u32 s45, s45, s21
	s_and_b64 s[20:21], vcc, exec
	s_cselect_b32 s1, s45, s29
	s_cselect_b32 s25, s44, s28
	s_add_u32 s46, s46, 0x40080
	s_addc_u32 s47, s47, 0
	s_add_u32 s58, s28, 0x100
	v_mov_b32_e32 v0, 0
	s_addc_u32 s59, s29, 0
	s_mov_b32 vcc_lo, -2
	v_mov_b32_e32 v1, v0
	v_mov_b64_e32 v[2:3], 0
	v_mov_b64_e32 v[4:5], 0
	v_mov_b64_e32 v[6:7], 0
	v_mov_b64_e32 v[8:9], 0
	v_mov_b64_e32 v[10:11], 0
	v_mov_b64_e32 v[16:17], 0
	v_mov_b64_e32 v[18:19], 0
	v_mov_b64_e32 v[24:25], 0
	v_mov_b64_e32 v[26:27], 0
	v_mov_b64_e32 v[32:33], 0
	v_mov_b64_e32 v[34:35], 0
	v_mov_b64_e32 v[40:41], 0
	v_mov_b64_e32 v[42:43], 0
	v_mov_b64_e32 v[48:49], 0
	v_mov_b64_e32 v[50:51], 0
	v_mov_b64_e32 v[12:13], 0
	v_mov_b64_e32 v[14:15], 0
	v_mov_b64_e32 v[20:21], 0
	v_mov_b64_e32 v[22:23], 0
	v_mov_b64_e32 v[28:29], 0
	v_mov_b64_e32 v[30:31], 0
	v_mov_b64_e32 v[36:37], 0
	v_mov_b64_e32 v[38:39], 0
	v_mov_b64_e32 v[44:45], 0
	v_mov_b64_e32 v[46:47], 0
	v_mov_b64_e32 v[52:53], 0
	v_mov_b64_e32 v[54:55], 0
	v_mov_b64_e32 v[56:57], 0
	v_mov_b64_e32 v[58:59], 0
	v_mov_b64_e32 v[60:61], 0
	v_mov_b64_e32 v[62:63], 0
	v_mov_b64_e32 v[64:65], 0
	v_mov_b64_e32 v[66:67], 0
	v_mov_b64_e32 v[68:69], 0
	v_mov_b64_e32 v[70:71], 0
	v_mov_b64_e32 v[76:77], 0
	v_mov_b64_e32 v[78:79], 0
	v_mov_b64_e32 v[84:85], 0
	v_mov_b64_e32 v[86:87], 0
	v_mov_b64_e32 v[88:89], 0
	v_mov_b64_e32 v[90:91], 0
	v_mov_b64_e32 v[96:97], 0
	v_mov_b64_e32 v[98:99], 0
	v_mov_b64_e32 v[104:105], 0
	v_mov_b64_e32 v[106:107], 0
	v_mov_b64_e32 v[112:113], 0
	v_mov_b64_e32 v[114:115], 0
	v_mov_b64_e32 v[72:73], 0
	v_mov_b64_e32 v[74:75], 0
	v_mov_b64_e32 v[80:81], 0
	v_mov_b64_e32 v[82:83], 0
	v_mov_b64_e32 v[92:93], 0
	v_mov_b64_e32 v[94:95], 0
	v_mov_b64_e32 v[100:101], 0
	v_mov_b64_e32 v[102:103], 0
	v_mov_b64_e32 v[108:109], 0
	v_mov_b64_e32 v[110:111], 0
	v_mov_b64_e32 v[116:117], 0
	v_mov_b64_e32 v[118:119], 0
	v_mov_b64_e32 v[120:121], 0
	v_mov_b64_e32 v[122:123], 0
	v_mov_b64_e32 v[124:125], 0
	v_mov_b64_e32 v[126:127], 0
	s_nop 0
.LBB0_292:
	s_add_u32 s20, s46, 0xfffc0080
	s_addc_u32 s21, s47, -1
	s_add_i32 s60, 0, 0x10000
	v_add_u32_e32 v138, s60, v141
	ds_read_b128 v[144:147], v138
	ds_read_b128 v[148:151], v138 offset:1024
	ds_read_b128 v[152:155], v138 offset:2048
	ds_read_b128 v[156:159], v138 offset:3072
	s_cmp_eq_u32 vcc_lo, 12
	s_cselect_b32 s49, s41, s21
	s_cselect_b32 s48, s24, s20
	s_cselect_b32 s29, s1, s59
	s_cselect_b32 s28, s25, s58
	s_add_i32 m0, s7, 0xc000
	ds_read_b128 v[160:163], v143
	ds_read_b128 v[164:167], v143 offset:1024
	ds_read_b128 v[168:171], v143 offset:2048
	ds_read_b128 v[172:175], v143 offset:3072
	ds_read_b128 v[198:201], v143 offset:4096
	ds_read_b128 v[202:205], v143 offset:5120
	ds_read_b128 v[206:209], v143 offset:6144
	ds_read_b128 v[210:213], v143 offset:7168
	global_load_lds_dwordx4 v134, s[46:47]
	s_add_i32 m0, s7, 0xe000
	s_nop 0
	global_load_lds_dwordx4 v136, s[46:47]
	s_waitcnt lgkmcnt(8)
	s_barrier
	s_waitcnt lgkmcnt(0)
	v_mfma_f32_16x16x32_bf16 v[124:127], v[144:147], v[160:163], v[124:127]
	v_mfma_f32_16x16x32_bf16 v[120:123], v[152:155], v[160:163], v[120:123]
	v_mfma_f32_16x16x32_bf16 v[116:119], v[144:147], v[168:171], v[116:119]
	v_mfma_f32_16x16x32_bf16 v[108:111], v[152:155], v[168:171], v[108:111]
	v_mfma_f32_16x16x32_bf16 v[100:103], v[144:147], v[198:201], v[100:103]
	v_mfma_f32_16x16x32_bf16 v[92:95], v[152:155], v[198:201], v[92:95]
	v_mfma_f32_16x16x32_bf16 v[80:83], v[144:147], v[206:209], v[80:83]
	v_mfma_f32_16x16x32_bf16 v[72:75], v[152:155], v[206:209], v[72:75]
	v_mfma_f32_16x16x32_bf16 v[124:127], v[148:151], v[164:167], v[124:127]
	v_mfma_f32_16x16x32_bf16 v[120:123], v[156:159], v[164:167], v[120:123]
	v_mfma_f32_16x16x32_bf16 v[116:119], v[148:151], v[172:175], v[116:119]
	v_mfma_f32_16x16x32_bf16 v[108:111], v[156:159], v[172:175], v[108:111]
	v_mfma_f32_16x16x32_bf16 v[100:103], v[148:151], v[202:205], v[100:103]
	v_mfma_f32_16x16x32_bf16 v[92:95], v[156:159], v[202:205], v[92:95]
	v_mfma_f32_16x16x32_bf16 v[80:83], v[148:151], v[210:213], v[80:83]
	v_mfma_f32_16x16x32_bf16 v[72:75], v[156:159], v[210:213], v[72:75]
	s_barrier
	s_add_i32 s61, 0, 0x14000
	v_add_u32_e32 v138, s61, v141
	s_add_i32 s20, s60, s6
	ds_read_b128 v[214:217], v138
	ds_read_b128 v[232:235], v138 offset:1024
	ds_read_b128 v[236:239], v138 offset:2048
	ds_read_b128 v[240:243], v138 offset:3072
	s_add_u32 s72, s28, s52
	s_addc_u32 s73, s29, s53
	s_mov_b32 m0, s20
	s_nop 0
	global_load_lds_dwordx4 v176, s[28:29]
	s_add_i32 m0, s20, 0x2000
	s_nop 0
	global_load_lds_dwordx4 v128, s[28:29]
	s_barrier
	s_waitcnt lgkmcnt(0)
	v_mfma_f32_16x16x32_bf16 v[112:115], v[214:217], v[160:163], v[112:115]
	v_mfma_f32_16x16x32_bf16 v[104:107], v[236:239], v[160:163], v[104:107]
	v_mfma_f32_16x16x32_bf16 v[96:99], v[214:217], v[168:171], v[96:99]
	v_mfma_f32_16x16x32_bf16 v[88:91], v[236:239], v[168:171], v[88:91]
	v_mfma_f32_16x16x32_bf16 v[84:87], v[214:217], v[198:201], v[84:87]
	v_mfma_f32_16x16x32_bf16 v[76:79], v[236:239], v[198:201], v[76:79]
	v_mfma_f32_16x16x32_bf16 v[68:71], v[214:217], v[206:209], v[68:71]
	v_mfma_f32_16x16x32_bf16 v[64:67], v[236:239], v[206:209], v[64:67]
	v_mfma_f32_16x16x32_bf16 v[112:115], v[232:235], v[164:167], v[112:115]
	v_mfma_f32_16x16x32_bf16 v[104:107], v[240:243], v[164:167], v[104:107]
	v_mfma_f32_16x16x32_bf16 v[96:99], v[232:235], v[172:175], v[96:99]
	v_mfma_f32_16x16x32_bf16 v[88:91], v[240:243], v[172:175], v[88:91]
	v_mfma_f32_16x16x32_bf16 v[84:87], v[232:235], v[202:205], v[84:87]
	v_mfma_f32_16x16x32_bf16 v[76:79], v[240:243], v[202:205], v[76:79]
	v_mfma_f32_16x16x32_bf16 v[68:71], v[232:235], v[210:213], v[68:71]
	v_mfma_f32_16x16x32_bf16 v[64:67], v[240:243], v[210:213], v[64:67]
	s_mov_b32 m0, s7
	s_add_u32 s94, s48, s52
	s_addc_u32 s95, s49, s53
	s_barrier
	ds_read_b128 v[160:163], v143 offset:16384
	ds_read_b128 v[164:167], v143 offset:17408
	ds_read_b128 v[168:171], v143 offset:18432
	ds_read_b128 v[172:175], v143 offset:19456
	ds_read_b128 v[198:201], v143 offset:20480
	ds_read_b128 v[202:205], v143 offset:21504
	ds_read_b128 v[206:209], v143 offset:22528
	ds_read_b128 v[210:213], v143 offset:23552
	global_load_lds_dwordx4 v132, s[48:49]
	s_mov_b32 m0, s9
	s_nop 0
	global_load_lds_dwordx4 v130, s[48:49]
	s_barrier
	s_waitcnt lgkmcnt(0)
	v_mfma_f32_16x16x32_bf16 v[60:63], v[144:147], v[160:163], v[60:63]
	v_mfma_f32_16x16x32_bf16 v[56:59], v[152:155], v[160:163], v[56:59]
	v_mfma_f32_16x16x32_bf16 v[52:55], v[144:147], v[168:171], v[52:55]
	v_mfma_f32_16x16x32_bf16 v[44:47], v[152:155], v[168:171], v[44:47]
	v_mfma_f32_16x16x32_bf16 v[36:39], v[144:147], v[198:201], v[36:39]
	v_mfma_f32_16x16x32_bf16 v[28:31], v[152:155], v[198:201], v[28:31]
	v_mfma_f32_16x16x32_bf16 v[20:23], v[144:147], v[206:209], v[20:23]
	v_mfma_f32_16x16x32_bf16 v[12:15], v[152:155], v[206:209], v[12:15]
	v_mfma_f32_16x16x32_bf16 v[60:63], v[148:151], v[164:167], v[60:63]
	v_mfma_f32_16x16x32_bf16 v[56:59], v[156:159], v[164:167], v[56:59]
	v_mfma_f32_16x16x32_bf16 v[52:55], v[148:151], v[172:175], v[52:55]
	v_mfma_f32_16x16x32_bf16 v[44:47], v[156:159], v[172:175], v[44:47]
	v_mfma_f32_16x16x32_bf16 v[36:39], v[148:151], v[202:205], v[36:39]
	v_mfma_f32_16x16x32_bf16 v[28:31], v[156:159], v[202:205], v[28:31]
	v_mfma_f32_16x16x32_bf16 v[20:23], v[148:151], v[210:213], v[20:23]
	v_mfma_f32_16x16x32_bf16 v[12:15], v[156:159], v[210:213], v[12:15]
	s_barrier
	s_add_u32 s20, s28, 0x40000
	s_addc_u32 s21, s29, 0
	s_add_i32 s60, s61, s6
	s_mov_b32 m0, s60
	s_nop 0
	global_load_lds_dwordx4 v176, s[20:21]
	s_add_i32 m0, s60, 0x2000
	s_nop 0
	global_load_lds_dwordx4 v128, s[20:21]
	s_waitcnt vmcnt(6)
	s_barrier
	v_mfma_f32_16x16x32_bf16 v[48:51], v[214:217], v[160:163], v[48:51]
	v_mfma_f32_16x16x32_bf16 v[40:43], v[236:239], v[160:163], v[40:43]
	v_mfma_f32_16x16x32_bf16 v[32:35], v[214:217], v[168:171], v[32:35]
	v_mfma_f32_16x16x32_bf16 v[24:27], v[236:239], v[168:171], v[24:27]
	v_mfma_f32_16x16x32_bf16 v[16:19], v[214:217], v[198:201], v[16:19]
	v_mfma_f32_16x16x32_bf16 v[8:11], v[236:239], v[198:201], v[8:11]
	v_mfma_f32_16x16x32_bf16 v[4:7], v[214:217], v[206:209], v[4:7]
	v_mfma_f32_16x16x32_bf16 v[0:3], v[236:239], v[206:209], v[0:3]
	v_mfma_f32_16x16x32_bf16 v[48:51], v[232:235], v[164:167], v[48:51]
	v_mfma_f32_16x16x32_bf16 v[40:43], v[240:243], v[164:167], v[40:43]
	v_mfma_f32_16x16x32_bf16 v[32:35], v[232:235], v[172:175], v[32:35]
	v_mfma_f32_16x16x32_bf16 v[24:27], v[240:243], v[172:175], v[24:27]
	v_mfma_f32_16x16x32_bf16 v[16:19], v[232:235], v[202:205], v[16:19]
	v_mfma_f32_16x16x32_bf16 v[8:11], v[240:243], v[202:205], v[8:11]
	v_mfma_f32_16x16x32_bf16 v[4:7], v[232:235], v[210:213], v[4:7]
	v_mfma_f32_16x16x32_bf16 v[0:3], v[240:243], v[210:213], v[0:3]
	s_add_i32 s60, 0, 0x18000
	v_add_u32_e32 v156, s60, v141
	s_barrier
	ds_read_b128 v[144:147], v156
	ds_read_b128 v[148:151], v156 offset:1024
	ds_read_b128 v[152:155], v156 offset:2048
	ds_read_b128 v[156:159], v156 offset:3072
	s_add_u32 s20, s48, 0x40000
	s_addc_u32 s21, s49, 0
	s_mov_b32 m0, s15
	ds_read_b128 v[160:163], v143 offset:32768
	ds_read_b128 v[164:167], v143 offset:33792
	ds_read_b128 v[168:171], v143 offset:34816
	ds_read_b128 v[172:175], v143 offset:35840
	ds_read_b128 v[198:201], v143 offset:36864
	ds_read_b128 v[202:205], v143 offset:37888
	ds_read_b128 v[206:209], v143 offset:38912
	ds_read_b128 v[210:213], v143 offset:39936
	global_load_lds_dwordx4 v132, s[20:21]
	s_mov_b32 m0, s34
	s_nop 0
	global_load_lds_dwordx4 v130, s[20:21]
	s_waitcnt lgkmcnt(8)
	s_barrier
	s_waitcnt lgkmcnt(0)
	v_mfma_f32_16x16x32_bf16 v[124:127], v[144:147], v[160:163], v[124:127]
	v_mfma_f32_16x16x32_bf16 v[120:123], v[152:155], v[160:163], v[120:123]
	v_mfma_f32_16x16x32_bf16 v[116:119], v[144:147], v[168:171], v[116:119]
	v_mfma_f32_16x16x32_bf16 v[108:111], v[152:155], v[168:171], v[108:111]
	v_mfma_f32_16x16x32_bf16 v[100:103], v[144:147], v[198:201], v[100:103]
	v_mfma_f32_16x16x32_bf16 v[92:95], v[152:155], v[198:201], v[92:95]
	v_mfma_f32_16x16x32_bf16 v[80:83], v[144:147], v[206:209], v[80:83]
	v_mfma_f32_16x16x32_bf16 v[72:75], v[152:155], v[206:209], v[72:75]
	v_mfma_f32_16x16x32_bf16 v[124:127], v[148:151], v[164:167], v[124:127]
	v_mfma_f32_16x16x32_bf16 v[120:123], v[156:159], v[164:167], v[120:123]
	v_mfma_f32_16x16x32_bf16 v[116:119], v[148:151], v[172:175], v[116:119]
	v_mfma_f32_16x16x32_bf16 v[108:111], v[156:159], v[172:175], v[108:111]
	v_mfma_f32_16x16x32_bf16 v[100:103], v[148:151], v[202:205], v[100:103]
	v_mfma_f32_16x16x32_bf16 v[92:95], v[156:159], v[202:205], v[92:95]
	v_mfma_f32_16x16x32_bf16 v[80:83], v[148:151], v[210:213], v[80:83]
	v_mfma_f32_16x16x32_bf16 v[72:75], v[156:159], v[210:213], v[72:75]
	s_barrier
	s_add_i32 s48, 0, 0x1c000
	s_add_i32 s20, s60, s6
	v_add_u32_e32 v184, s48, v141
	s_mov_b32 m0, s20
	ds_read_b128 v[214:217], v184
	ds_read_b128 v[232:235], v184 offset:1024
	ds_read_b128 v[236:239], v184 offset:2048
	ds_read_b128 v[240:243], v184 offset:3072
	global_load_lds_dwordx4 v176, s[72:73]
	s_add_i32 m0, s20, 0x2000
	s_nop 0
	global_load_lds_dwordx4 v128, s[72:73]
	s_barrier
	s_waitcnt lgkmcnt(0)
	v_mfma_f32_16x16x32_bf16 v[112:115], v[214:217], v[160:163], v[112:115]
	v_mfma_f32_16x16x32_bf16 v[104:107], v[236:239], v[160:163], v[104:107]
	v_mfma_f32_16x16x32_bf16 v[96:99], v[214:217], v[168:171], v[96:99]
	v_mfma_f32_16x16x32_bf16 v[88:91], v[236:239], v[168:171], v[88:91]
	v_mfma_f32_16x16x32_bf16 v[84:87], v[214:217], v[198:201], v[84:87]
	v_mfma_f32_16x16x32_bf16 v[76:79], v[236:239], v[198:201], v[76:79]
	v_mfma_f32_16x16x32_bf16 v[68:71], v[214:217], v[206:209], v[68:71]
	v_mfma_f32_16x16x32_bf16 v[64:67], v[236:239], v[206:209], v[64:67]
	v_mfma_f32_16x16x32_bf16 v[112:115], v[232:235], v[164:167], v[112:115]
	v_mfma_f32_16x16x32_bf16 v[104:107], v[240:243], v[164:167], v[104:107]
	v_mfma_f32_16x16x32_bf16 v[96:99], v[232:235], v[172:175], v[96:99]
	v_mfma_f32_16x16x32_bf16 v[88:91], v[240:243], v[172:175], v[88:91]
	v_mfma_f32_16x16x32_bf16 v[84:87], v[232:235], v[202:205], v[84:87]
	v_mfma_f32_16x16x32_bf16 v[76:79], v[240:243], v[202:205], v[76:79]
	v_mfma_f32_16x16x32_bf16 v[68:71], v[232:235], v[210:213], v[68:71]
	v_mfma_f32_16x16x32_bf16 v[64:67], v[240:243], v[210:213], v[64:67]
	s_mov_b32 m0, s51
	s_barrier
	ds_read_b128 v[160:163], v143 offset:49152
	ds_read_b128 v[164:167], v143 offset:50176
	ds_read_b128 v[168:171], v143 offset:51200
	ds_read_b128 v[172:175], v143 offset:52224
	ds_read_b128 v[198:201], v143 offset:53248
	ds_read_b128 v[202:205], v143 offset:54272
	ds_read_b128 v[206:209], v143 offset:55296
	ds_read_b128 v[210:213], v143 offset:56320
	global_load_lds_dwordx4 v132, s[94:95]
	s_mov_b32 m0, s54
	s_nop 0
	global_load_lds_dwordx4 v130, s[94:95]
	s_barrier
	s_waitcnt lgkmcnt(0)
	v_mfma_f32_16x16x32_bf16 v[60:63], v[144:147], v[160:163], v[60:63]
	v_mfma_f32_16x16x32_bf16 v[56:59], v[152:155], v[160:163], v[56:59]
	v_mfma_f32_16x16x32_bf16 v[52:55], v[144:147], v[168:171], v[52:55]
	v_mfma_f32_16x16x32_bf16 v[44:47], v[152:155], v[168:171], v[44:47]
	v_mfma_f32_16x16x32_bf16 v[36:39], v[144:147], v[198:201], v[36:39]
	v_mfma_f32_16x16x32_bf16 v[28:31], v[152:155], v[198:201], v[28:31]
	v_mfma_f32_16x16x32_bf16 v[20:23], v[144:147], v[206:209], v[20:23]
	v_mfma_f32_16x16x32_bf16 v[12:15], v[152:155], v[206:209], v[12:15]
	v_mfma_f32_16x16x32_bf16 v[60:63], v[148:151], v[164:167], v[60:63]
	v_mfma_f32_16x16x32_bf16 v[56:59], v[156:159], v[164:167], v[56:59]
	v_mfma_f32_16x16x32_bf16 v[52:55], v[148:151], v[172:175], v[52:55]
	v_mfma_f32_16x16x32_bf16 v[44:47], v[156:159], v[172:175], v[44:47]
	v_mfma_f32_16x16x32_bf16 v[36:39], v[148:151], v[202:205], v[36:39]
	v_mfma_f32_16x16x32_bf16 v[28:31], v[156:159], v[202:205], v[28:31]
	v_mfma_f32_16x16x32_bf16 v[20:23], v[148:151], v[210:213], v[20:23]
	v_mfma_f32_16x16x32_bf16 v[12:15], v[156:159], v[210:213], v[12:15]
	s_barrier
	s_add_u32 s20, s28, 0x40080
	s_addc_u32 s21, s29, 0
	s_add_i32 s28, s48, s6
	s_mov_b32 m0, s28
	s_nop 0
	global_load_lds_dwordx4 v176, s[20:21]
	s_add_i32 m0, s28, 0x2000
	s_nop 0
	global_load_lds_dwordx4 v128, s[20:21]
	s_waitcnt vmcnt(6)
	s_barrier
	v_mfma_f32_16x16x32_bf16 v[48:51], v[214:217], v[160:163], v[48:51]
	v_mfma_f32_16x16x32_bf16 v[40:43], v[236:239], v[160:163], v[40:43]
	v_mfma_f32_16x16x32_bf16 v[32:35], v[214:217], v[168:171], v[32:35]
	v_mfma_f32_16x16x32_bf16 v[24:27], v[236:239], v[168:171], v[24:27]
	v_mfma_f32_16x16x32_bf16 v[16:19], v[214:217], v[198:201], v[16:19]
	v_mfma_f32_16x16x32_bf16 v[8:11], v[236:239], v[198:201], v[8:11]
	v_mfma_f32_16x16x32_bf16 v[4:7], v[214:217], v[206:209], v[4:7]
	v_mfma_f32_16x16x32_bf16 v[0:3], v[236:239], v[206:209], v[0:3]
	v_mfma_f32_16x16x32_bf16 v[48:51], v[232:235], v[164:167], v[48:51]
	v_mfma_f32_16x16x32_bf16 v[40:43], v[240:243], v[164:167], v[40:43]
	v_mfma_f32_16x16x32_bf16 v[32:35], v[232:235], v[172:175], v[32:35]
	v_mfma_f32_16x16x32_bf16 v[24:27], v[240:243], v[172:175], v[24:27]
	v_mfma_f32_16x16x32_bf16 v[16:19], v[232:235], v[202:205], v[16:19]
	v_mfma_f32_16x16x32_bf16 v[8:11], v[240:243], v[202:205], v[8:11]
	v_mfma_f32_16x16x32_bf16 v[4:7], v[232:235], v[210:213], v[4:7]
	v_mfma_f32_16x16x32_bf16 v[0:3], v[240:243], v[210:213], v[0:3]
	s_add_i32 vcc_lo, vcc_lo, 2
	s_add_u32 s46, s46, 0x100
	s_addc_u32 s47, s47, 0
	s_add_u32 s58, s58, 0x100
	s_addc_u32 s59, s59, 0
	s_cmp_gt_u32 vcc_lo, 13
	s_barrier
	s_cbranch_scc0 .LBB0_292
	s_nop 0
	v_lshl_add_u32 v144, s57, 8, v140
	v_lshl_or_b32 v138, s2, 8, v142
	v_ashrrev_i32_e32 v145, 31, v144
	v_readlane_b32 s20, v254, 43
	v_ashrrev_i32_e32 v139, 31, v138
	v_lshlrev_b64 v[146:147], 16, v[144:145]
	v_readlane_b32 s21, v254, 44
	v_lshlrev_b64 v[148:149], 1, v[138:139]
	v_cvt_pk_bf16_f32 v124, v124, v125
	v_cvt_pk_bf16_f32 v125, v126, v127
	v_cvt_pk_bf16_f32 v126, v120, v121
	v_cvt_pk_bf16_f32 v127, v122, v123
	s_nop 0
	v_lshl_add_u64 v[146:147], s[20:21], 0, v[146:147]
	v_lshl_add_u64 v[138:139], v[146:147], 0, v[148:149]
	global_store_dwordx4 v[138:139], v[124:127], off
	v_cvt_pk_bf16_f32 v112, v112, v113
	v_cvt_pk_bf16_f32 v113, v114, v115
	v_cvt_pk_bf16_f32 v114, v104, v105
	v_or_b32_e32 v104, 16, v144
	v_ashrrev_i32_e32 v105, 31, v104
	v_lshlrev_b64 v[104:105], 16, v[104:105]
	v_lshl_add_u64 v[104:105], s[20:21], 0, v[104:105]
	v_cvt_pk_bf16_f32 v115, v106, v107
	global_store_dwordx4 v[138:139], v[112:115], off offset:256
	s_mov_b32 s1, 0x900000
	s_mov_b32 s2, s0
	v_lshl_add_u64 v[112:113], v[104:105], 0, v[148:149]
	v_cvt_pk_bf16_f32 v104, v116, v117
	v_cvt_pk_bf16_f32 v105, v118, v119
	v_cvt_pk_bf16_f32 v106, v108, v109
	v_cvt_pk_bf16_f32 v107, v110, v111
	global_store_dwordx4 v[112:113], v[104:107], off
	v_cvt_pk_bf16_f32 v96, v96, v97
	v_cvt_pk_bf16_f32 v97, v98, v99
	v_cvt_pk_bf16_f32 v98, v88, v89
	v_or_b32_e32 v88, 32, v144
	v_ashrrev_i32_e32 v89, 31, v88
	v_lshlrev_b64 v[88:89], 16, v[88:89]
	v_lshl_add_u64 v[88:89], s[20:21], 0, v[88:89]
	v_cvt_pk_bf16_f32 v99, v90, v91
	global_store_dwordx4 v[112:113], v[96:99], off offset:256
	s_mov_b32 s57, s40
	s_mov_b64 s[28:29], s[44:45]
	v_lshl_add_u64 v[96:97], v[88:89], 0, v[148:149]
	v_cvt_pk_bf16_f32 v88, v100, v101
	v_cvt_pk_bf16_f32 v89, v102, v103
	v_cvt_pk_bf16_f32 v90, v92, v93
	v_cvt_pk_bf16_f32 v91, v94, v95
	global_store_dwordx4 v[96:97], v[88:91], off
	v_cvt_pk_bf16_f32 v84, v84, v85
	v_cvt_pk_bf16_f32 v85, v86, v87
	v_cvt_pk_bf16_f32 v86, v76, v77
	v_or_b32_e32 v76, 48, v144
	v_ashrrev_i32_e32 v77, 31, v76
	v_lshlrev_b64 v[76:77], 16, v[76:77]
	v_lshl_add_u64 v[76:77], s[20:21], 0, v[76:77]
	v_cvt_pk_bf16_f32 v87, v78, v79
	global_store_dwordx4 v[96:97], v[84:87], off offset:256
	s_mov_b64 s[20:21], 0x800000
	s_mov_b64 s[46:47], s[42:43]
	v_lshl_add_u64 v[84:85], v[76:77], 0, v[148:149]
	v_cvt_pk_bf16_f32 v76, v80, v81
	v_cvt_pk_bf16_f32 v77, v82, v83
	v_cvt_pk_bf16_f32 v78, v72, v73
	v_cvt_pk_bf16_f32 v79, v74, v75
	global_store_dwordx4 v[84:85], v[76:79], off
	v_cvt_pk_bf16_f32 v68, v68, v69
	v_cvt_pk_bf16_f32 v69, v70, v71
	v_cvt_pk_bf16_f32 v70, v64, v65
	v_cvt_pk_bf16_f32 v71, v66, v67
	global_store_dwordx4 v[84:85], v[68:71], off offset:256
	v_cvt_pk_bf16_f32 v60, v60, v61
	v_cvt_pk_bf16_f32 v61, v62, v63
	v_cvt_pk_bf16_f32 v62, v56, v57
	v_add_co_u32_e32 v56, vcc, s23, v138
	v_lshl_add_u64 v[64:65], v[138:139], 0, s[20:21]
	s_nop 0
	v_addc_co_u32_e32 v57, vcc, 0, v139, vcc
	v_cvt_pk_bf16_f32 v63, v58, v59
	global_store_dwordx4 v[56:57], v[60:63], off
	v_cvt_pk_bf16_f32 v48, v48, v49
	v_cvt_pk_bf16_f32 v49, v50, v51
	v_cvt_pk_bf16_f32 v50, v40, v41
	v_cvt_pk_bf16_f32 v51, v42, v43
	global_store_dwordx4 v[64:65], v[48:51], off offset:256
	s_mov_b64 s[20:21], 0x900000
	v_cvt_pk_bf16_f32 v40, v52, v53
	v_cvt_pk_bf16_f32 v41, v54, v55
	v_cvt_pk_bf16_f32 v42, v44, v45
	v_add_co_u32_e32 v44, vcc, s1, v138
	v_lshl_add_u64 v[48:49], v[138:139], 0, s[20:21]
	s_nop 0
	v_addc_co_u32_e32 v45, vcc, 0, v139, vcc
	s_mov_b32 s1, 0xa00000
	v_cvt_pk_bf16_f32 v43, v46, v47
	global_store_dwordx4 v[44:45], v[40:43], off
	v_cvt_pk_bf16_f32 v32, v32, v33
	v_cvt_pk_bf16_f32 v33, v34, v35
	v_cvt_pk_bf16_f32 v34, v24, v25
	v_cvt_pk_bf16_f32 v35, v26, v27
	global_store_dwordx4 v[48:49], v[32:35], off offset:256
	s_mov_b64 s[20:21], 0xa00000
	v_cvt_pk_bf16_f32 v24, v36, v37
	v_cvt_pk_bf16_f32 v25, v38, v39
	v_cvt_pk_bf16_f32 v26, v28, v29
	v_add_co_u32_e32 v28, vcc, s1, v138
	v_lshl_add_u64 v[32:33], v[138:139], 0, s[20:21]
	s_nop 0
	v_addc_co_u32_e32 v29, vcc, 0, v139, vcc
	s_mov_b32 s1, 0xb00000
	v_cvt_pk_bf16_f32 v27, v30, v31
	global_store_dwordx4 v[28:29], v[24:27], off
	v_cvt_pk_bf16_f32 v16, v16, v17
	v_cvt_pk_bf16_f32 v17, v18, v19
	v_cvt_pk_bf16_f32 v18, v8, v9
	v_cvt_pk_bf16_f32 v19, v10, v11
	global_store_dwordx4 v[32:33], v[16:19], off offset:256
	v_cvt_pk_bf16_f32 v8, v20, v21
	v_cvt_pk_bf16_f32 v9, v22, v23
	v_cvt_pk_bf16_f32 v10, v12, v13
	v_add_co_u32_e32 v12, vcc, s1, v138
	s_mov_b64 s[20:21], 0xb00000
	s_nop 0
	v_addc_co_u32_e32 v13, vcc, 0, v139, vcc
	v_lshl_add_u64 v[16:17], v[138:139], 0, s[20:21]
	s_and_b64 vcc, exec, s[38:39]
	v_cvt_pk_bf16_f32 v11, v14, v15
	global_store_dwordx4 v[12:13], v[8:11], off
	v_cvt_pk_bf16_f32 v4, v4, v5
	v_cvt_pk_bf16_f32 v5, v6, v7
	v_cvt_pk_bf16_f32 v6, v0, v1
	v_cvt_pk_bf16_f32 v7, v2, v3
	global_store_dwordx4 v[16:17], v[4:7], off offset:256
	s_cbranch_vccz .LBB0_285
	s_waitcnt vmcnt(0)
	v_readlane_b32 s54, v253, 37
	s_cmpk_gt_u32 s3, 0xff
	v_readlane_b32 s55, v253, 38
	s_cbranch_scc1 .LBB0_296
	s_barrier
